# attention row-max via v_max3 chains instead of canonicalize+max pairs (on top of prefetch fix)
# baseline (speedup 1.0000x reference)
.LBB0_1738:
	s_nop 4
	v_max3_f32 v183, v80, v81, v82
	v_max3_f32 v184, v88, v89, v90
	v_max3_f32 v183, v183, v83, v84
	v_max3_f32 v184, v184, v91, v92
	v_max3_f32 v183, v183, v85, v86
	v_max3_f32 v184, v184, v93, v94
	v_max_f32_e32 v183, v183, v87
	v_max_f32_e32 v184, v184, v95
	v_max3_f32 v181, v64, v65, v66
	v_max3_f32 v182, v72, v73, v74
	v_max3_f32 v181, v181, v67, v68
	v_max3_f32 v182, v182, v75, v76
	v_max3_f32 v181, v181, v69, v70
	v_max3_f32 v182, v182, v77, v78
	v_max_f32_e32 v181, v181, v71
	v_max_f32_e32 v182, v182, v79
	v_max3_f32 v181, v181, v182, v183
	v_max_f32_e32 v181, v181, v184
	s_or_b64 s[0:1], s[8:9], s[0:1]
	v_cndmask_b32_e64 v181, v159, v181, s[0:1]
	ds_bpermute_b32 v182, v169, v181
	s_waitcnt lgkmcnt(0)
	v_max3_f32 v181, v154, v181, v182
	v_sub_f32_e32 v154, v154, v181
	v_exp_f32_e32 v154, v154
	s_nop 0
	v_cmp_neq_f32_e32 vcc, 1.0, v154
	s_cbranch_vccz .LBB0_1727
	v_pk_mul_f32 v[62:63], v[62:63], v[154:155] op_sel_hi:[1,0]
	v_pk_mul_f32 v[60:61], v[60:61], v[154:155] op_sel_hi:[1,0]
	v_pk_mul_f32 v[58:59], v[58:59], v[154:155] op_sel_hi:[1,0]
	v_pk_mul_f32 v[56:57], v[56:57], v[154:155] op_sel_hi:[1,0]
	v_pk_mul_f32 v[54:55], v[54:55], v[154:155] op_sel_hi:[1,0]
	v_pk_mul_f32 v[52:53], v[52:53], v[154:155] op_sel_hi:[1,0]
	v_pk_mul_f32 v[50:51], v[50:51], v[154:155] op_sel_hi:[1,0]
	v_pk_mul_f32 v[48:49], v[48:49], v[154:155] op_sel_hi:[1,0]
	v_pk_mul_f32 v[46:47], v[46:47], v[154:155] op_sel_hi:[1,0]
	v_pk_mul_f32 v[44:45], v[44:45], v[154:155] op_sel_hi:[1,0]
	v_pk_mul_f32 v[42:43], v[42:43], v[154:155] op_sel_hi:[1,0]
	v_pk_mul_f32 v[40:41], v[40:41], v[154:155] op_sel_hi:[1,0]
	v_pk_mul_f32 v[38:39], v[38:39], v[154:155] op_sel_hi:[1,0]
	v_pk_mul_f32 v[36:37], v[36:37], v[154:155] op_sel_hi:[1,0]
	v_pk_mul_f32 v[34:35], v[34:35], v[154:155] op_sel_hi:[1,0]
	v_pk_mul_f32 v[32:33], v[32:33], v[154:155] op_sel_hi:[1,0]
	v_pk_mul_f32 v[30:31], v[30:31], v[154:155] op_sel_hi:[1,0]
	v_pk_mul_f32 v[28:29], v[28:29], v[154:155] op_sel_hi:[1,0]
	v_pk_mul_f32 v[26:27], v[26:27], v[154:155] op_sel_hi:[1,0]
	v_pk_mul_f32 v[24:25], v[24:25], v[154:155] op_sel_hi:[1,0]
	v_pk_mul_f32 v[22:23], v[22:23], v[154:155] op_sel_hi:[1,0]
	v_pk_mul_f32 v[20:21], v[20:21], v[154:155] op_sel_hi:[1,0]
	v_pk_mul_f32 v[18:19], v[18:19], v[154:155] op_sel_hi:[1,0]
	v_pk_mul_f32 v[16:17], v[16:17], v[154:155] op_sel_hi:[1,0]
	v_pk_mul_f32 v[14:15], v[14:15], v[154:155] op_sel_hi:[1,0]
	v_pk_mul_f32 v[12:13], v[12:13], v[154:155] op_sel_hi:[1,0]
	v_pk_mul_f32 v[10:11], v[10:11], v[154:155] op_sel_hi:[1,0]
	v_pk_mul_f32 v[8:9], v[8:9], v[154:155] op_sel_hi:[1,0]
	v_pk_mul_f32 v[6:7], v[6:7], v[154:155] op_sel_hi:[1,0]
	v_pk_mul_f32 v[4:5], v[4:5], v[154:155] op_sel_hi:[1,0]
	v_pk_mul_f32 v[2:3], v[2:3], v[154:155] op_sel_hi:[1,0]
	v_pk_mul_f32 v[0:1], v[0:1], v[154:155] op_sel_hi:[1,0]
	s_branch .LBB0_1727

.LBB0_1749:
	s_nop 4
	v_max3_f32 v98, v80, v81, v82
	v_max3_f32 v99, v88, v89, v90
	v_max3_f32 v98, v98, v83, v84
	v_max3_f32 v99, v99, v91, v92
	v_max3_f32 v98, v98, v85, v86
	v_max3_f32 v99, v99, v93, v94
	v_max_f32_e32 v98, v98, v87
	v_max_f32_e32 v99, v99, v95
	v_max3_f32 v96, v64, v65, v66
	v_max3_f32 v97, v72, v73, v74
	v_max3_f32 v96, v96, v67, v68
	v_max3_f32 v97, v97, v75, v76
	v_max3_f32 v96, v96, v69, v70
	v_max3_f32 v97, v97, v77, v78
	v_max_f32_e32 v96, v96, v71
	v_max_f32_e32 v97, v97, v79
	v_max3_f32 v96, v96, v97, v98
	v_max_f32_e32 v96, v96, v99
	s_or_b64 s[0:1], s[8:9], s[0:1]
	v_cndmask_b32_e64 v96, v159, v96, s[0:1]
	ds_bpermute_b32 v97, v169, v96
	s_waitcnt lgkmcnt(0)
	v_max3_f32 v97, v154, v96, v97
	v_sub_f32_e32 v96, v154, v97
	v_exp_f32_e32 v96, v96
	s_nop 0
	v_cmp_neq_f32_e32 vcc, 1.0, v96
	s_cbranch_vccz .LBB0_1751
	v_pk_mul_f32 v[62:63], v[62:63], v[96:97] op_sel_hi:[1,0]
	v_pk_mul_f32 v[60:61], v[60:61], v[96:97] op_sel_hi:[1,0]
	v_pk_mul_f32 v[58:59], v[58:59], v[96:97] op_sel_hi:[1,0]
	v_pk_mul_f32 v[56:57], v[56:57], v[96:97] op_sel_hi:[1,0]
	v_pk_mul_f32 v[54:55], v[54:55], v[96:97] op_sel_hi:[1,0]
	v_pk_mul_f32 v[52:53], v[52:53], v[96:97] op_sel_hi:[1,0]
	v_pk_mul_f32 v[50:51], v[50:51], v[96:97] op_sel_hi:[1,0]
	v_pk_mul_f32 v[48:49], v[48:49], v[96:97] op_sel_hi:[1,0]
	v_pk_mul_f32 v[46:47], v[46:47], v[96:97] op_sel_hi:[1,0]
	v_pk_mul_f32 v[44:45], v[44:45], v[96:97] op_sel_hi:[1,0]
	v_pk_mul_f32 v[42:43], v[42:43], v[96:97] op_sel_hi:[1,0]
	v_pk_mul_f32 v[40:41], v[40:41], v[96:97] op_sel_hi:[1,0]
	v_pk_mul_f32 v[38:39], v[38:39], v[96:97] op_sel_hi:[1,0]
	v_pk_mul_f32 v[36:37], v[36:37], v[96:97] op_sel_hi:[1,0]
	v_pk_mul_f32 v[34:35], v[34:35], v[96:97] op_sel_hi:[1,0]
	v_pk_mul_f32 v[32:33], v[32:33], v[96:97] op_sel_hi:[1,0]
	v_pk_mul_f32 v[30:31], v[30:31], v[96:97] op_sel_hi:[1,0]
	v_pk_mul_f32 v[28:29], v[28:29], v[96:97] op_sel_hi:[1,0]
	v_pk_mul_f32 v[26:27], v[26:27], v[96:97] op_sel_hi:[1,0]
	v_pk_mul_f32 v[24:25], v[24:25], v[96:97] op_sel_hi:[1,0]
	v_pk_mul_f32 v[22:23], v[22:23], v[96:97] op_sel_hi:[1,0]
	v_pk_mul_f32 v[20:21], v[20:21], v[96:97] op_sel_hi:[1,0]
	v_pk_mul_f32 v[18:19], v[18:19], v[96:97] op_sel_hi:[1,0]
	v_pk_mul_f32 v[16:17], v[16:17], v[96:97] op_sel_hi:[1,0]
	v_pk_mul_f32 v[14:15], v[14:15], v[96:97] op_sel_hi:[1,0]
	v_pk_mul_f32 v[12:13], v[12:13], v[96:97] op_sel_hi:[1,0]
	v_pk_mul_f32 v[10:11], v[10:11], v[96:97] op_sel_hi:[1,0]
	v_pk_mul_f32 v[8:9], v[8:9], v[96:97] op_sel_hi:[1,0]
	v_pk_mul_f32 v[6:7], v[6:7], v[96:97] op_sel_hi:[1,0]
	v_pk_mul_f32 v[4:5], v[4:5], v[96:97] op_sel_hi:[1,0]
	v_pk_mul_f32 v[2:3], v[2:3], v[96:97] op_sel_hi:[1,0]
	v_pk_mul_f32 v[0:1], v[0:1], v[96:97] op_sel_hi:[1,0]

.LBB0_1792:
	s_nop 4
	v_max3_f32 v98, v80, v81, v82
	v_max3_f32 v99, v88, v89, v90
	v_max3_f32 v98, v98, v83, v84
	v_max3_f32 v99, v99, v91, v92
	v_max3_f32 v98, v98, v85, v86
	v_max3_f32 v99, v99, v93, v94
	v_max_f32_e32 v98, v98, v87
	v_max_f32_e32 v99, v99, v95
	v_max3_f32 v96, v64, v65, v66
	v_max3_f32 v97, v72, v73, v74
	v_max3_f32 v96, v96, v67, v68
	v_max3_f32 v97, v97, v75, v76
	v_max3_f32 v96, v96, v69, v70
	v_max3_f32 v97, v97, v77, v78
	v_max_f32_e32 v96, v96, v71
	v_max_f32_e32 v97, v97, v79
	v_max3_f32 v96, v96, v97, v98
	v_max_f32_e32 v96, v96, v99
	s_or_b64 s[0:1], s[8:9], s[0:1]
	v_cndmask_b32_e64 v96, v159, v96, s[0:1]
	ds_bpermute_b32 v97, v169, v96
	s_waitcnt lgkmcnt(0)
	v_max3_f32 v97, v154, v96, v97
	v_sub_f32_e32 v96, v154, v97
	v_exp_f32_e32 v96, v96
	s_nop 0
	v_cmp_neq_f32_e32 vcc, 1.0, v96
	s_cbranch_vccz .LBB0_1710
	v_pk_mul_f32 v[62:63], v[62:63], v[96:97] op_sel_hi:[1,0]
	v_pk_mul_f32 v[60:61], v[60:61], v[96:97] op_sel_hi:[1,0]
	v_pk_mul_f32 v[58:59], v[58:59], v[96:97] op_sel_hi:[1,0]
	v_pk_mul_f32 v[56:57], v[56:57], v[96:97] op_sel_hi:[1,0]
	v_pk_mul_f32 v[54:55], v[54:55], v[96:97] op_sel_hi:[1,0]
	v_pk_mul_f32 v[52:53], v[52:53], v[96:97] op_sel_hi:[1,0]
	v_pk_mul_f32 v[50:51], v[50:51], v[96:97] op_sel_hi:[1,0]
	v_pk_mul_f32 v[48:49], v[48:49], v[96:97] op_sel_hi:[1,0]
	v_pk_mul_f32 v[46:47], v[46:47], v[96:97] op_sel_hi:[1,0]
	v_pk_mul_f32 v[44:45], v[44:45], v[96:97] op_sel_hi:[1,0]
	v_pk_mul_f32 v[42:43], v[42:43], v[96:97] op_sel_hi:[1,0]
	v_pk_mul_f32 v[40:41], v[40:41], v[96:97] op_sel_hi:[1,0]
	v_pk_mul_f32 v[38:39], v[38:39], v[96:97] op_sel_hi:[1,0]
	v_pk_mul_f32 v[36:37], v[36:37], v[96:97] op_sel_hi:[1,0]
	v_pk_mul_f32 v[34:35], v[34:35], v[96:97] op_sel_hi:[1,0]
	v_pk_mul_f32 v[32:33], v[32:33], v[96:97] op_sel_hi:[1,0]
	v_pk_mul_f32 v[30:31], v[30:31], v[96:97] op_sel_hi:[1,0]
	v_pk_mul_f32 v[28:29], v[28:29], v[96:97] op_sel_hi:[1,0]
	v_pk_mul_f32 v[26:27], v[26:27], v[96:97] op_sel_hi:[1,0]
	v_pk_mul_f32 v[24:25], v[24:25], v[96:97] op_sel_hi:[1,0]
	v_pk_mul_f32 v[22:23], v[22:23], v[96:97] op_sel_hi:[1,0]
	v_pk_mul_f32 v[20:21], v[20:21], v[96:97] op_sel_hi:[1,0]
	v_pk_mul_f32 v[18:19], v[18:19], v[96:97] op_sel_hi:[1,0]
	v_pk_mul_f32 v[16:17], v[16:17], v[96:97] op_sel_hi:[1,0]
	v_pk_mul_f32 v[14:15], v[14:15], v[96:97] op_sel_hi:[1,0]
	v_pk_mul_f32 v[12:13], v[12:13], v[96:97] op_sel_hi:[1,0]
	v_pk_mul_f32 v[10:11], v[10:11], v[96:97] op_sel_hi:[1,0]
	v_pk_mul_f32 v[8:9], v[8:9], v[96:97] op_sel_hi:[1,0]
	v_pk_mul_f32 v[6:7], v[6:7], v[96:97] op_sel_hi:[1,0]
	v_pk_mul_f32 v[4:5], v[4:5], v[96:97] op_sel_hi:[1,0]
	v_pk_mul_f32 v[2:3], v[2:3], v[96:97] op_sel_hi:[1,0]
	v_pk_mul_f32 v[0:1], v[0:1], v[96:97] op_sel_hi:[1,0]
	s_branch .LBB0_1710
